# P4: each wave takes 64 consecutive token rows and reuses the loaded row as the next row's previous-token operands (5 loads per row instead of 8)
# speedup vs baseline: 1.0011x; 1.0011x over previous
.LBB0_465:
	s_cmp_lt_i32 s84, 5
	s_cselect_b64 s[4:5], -1, 0
	s_and_b64 s[10:11], s[4:5], s[0:1]
	s_andn2_b64 vcc, exec, s[10:11]
	s_cbranch_vccnz .LBB0_474
	s_ashr_i32 s12, s72, 2
	s_lshl_b32 s12, s12, 6
	s_cmpk_gt_i32 s12, 0x7fff
	s_cbranch_scc1 .LBB0_474
	s_lshl_b32 s0, s50, 8
	s_and_b32 s0, s0, 0x300
	v_lshl_or_b32 v1, v152, 2, s0
	v_readlane_b32 s16, v239, 10
	v_lshlrev_b32_e32 v34, 2, v1
	v_mov_b32_e32 v35, 0
	v_readlane_b32 s20, v239, 14
	v_readlane_b32 s21, v239, 15
	s_movk_i32 s0, 0x2000
	v_readlane_b32 s52, v239, 28
	v_lshl_add_u64 v[18:19], s[20:21], 0, v[34:35]
	v_add_co_u32_e32 v20, vcc, s0, v18
	s_movk_i32 s0, 0x1000
	s_nop 0
	v_addc_co_u32_e32 v21, vcc, 0, v19, vcc
	v_add_co_u32_e32 v22, vcc, s0, v18
	v_readlane_b32 s54, v239, 30
	v_readlane_b32 s55, v239, 31
	v_readlane_b32 s26, v239, 20
	v_readlane_b32 s27, v239, 21
	v_addc_co_u32_e32 v23, vcc, 0, v19, vcc
	v_readlane_b32 s53, v239, 29
	v_readlane_b32 s56, v239, 32
	v_readlane_b32 s57, v239, 33
	global_load_dwordx4 v[2:5], v34, s[54:55]
	s_nop 1
	global_load_dwordx4 v[6:9], v34, s[52:53]
	v_readlane_b32 s22, v239, 16
	v_readlane_b32 s23, v239, 17
	global_load_dwordx4 v[10:13], v34, s[26:27]
	s_nop 3
	global_load_dwordx4 v[14:17], v34, s[22:23]
	s_nop 0
	global_load_dwordx4 v[18:21], v[20:21], off
	s_nop 0
	global_load_dwordx4 v[22:25], v[22:23], off
	s_nop 0
	global_load_dwordx4 v[26:29], v34, s[56:57]
	global_load_dwordx4 v[30:33], v34, s[20:21]
	s_ashr_i32 s13, s12, 31
	s_mov_b32 s14, 1
	v_and_b32_e32 v34, 15, v153
	s_lshl_b64 s[4:5], s[12:13], 6
	v_cmp_eq_u32_e64 s[0:1], 0, v34
	v_lshrrev_b32_e32 v34, 4, v1
	s_add_u32 s4, s78, s4
	v_and_b32_e32 v34, 60, v34
	s_addc_u32 s5, s79, s5
	v_readlane_b32 s17, v239, 11
	v_lshl_add_u64 v[36:37], s[4:5], 0, v[34:35]
	s_mov_b64 s[4:5], 0x300000
	s_ashr_i32 s15, s14, 31
	v_readlane_b32 s18, v239, 12
	v_lshl_add_u64 v[36:37], v[36:37], 0, s[4:5]
	s_lshl_b64 s[16:17], s[14:15], 6
	s_lshl_b64 s[4:5], s[12:13], 11
	v_readlane_b32 s19, v239, 13
	s_add_u32 s18, s78, s4
	s_addc_u32 s19, s79, s5
	s_lshl_b64 s[20:21], s[14:15], 11
	s_add_u32 s22, s70, s4
	v_readlane_b32 s24, v239, 18
	s_addc_u32 s23, s71, s5
	s_mul_i32 s5, s12, 0x1a00
	v_readlane_b32 s25, v239, 19
	v_readlane_b32 s28, v239, 22
	v_readlane_b32 s29, v239, 23
	v_readlane_b32 s30, v239, 24
	v_readlane_b32 s31, v239, 25
	s_mul_hi_i32 s4, s12, 0x1a00
	s_add_u32 s24, s78, s5
	v_lshlrev_b32_e32 v34, 1, v1
	s_addc_u32 s25, s79, s4
	s_movk_i32 s13, 0x1a00
	s_mul_hi_i32 s15, s14, 0x1a00
	s_mov_b32 s26, 0xbfb8aa3b
	s_mov_b32 s27, 0x800000
	s_mov_b32 s28, 0x3f317217
	s_mov_b32 s29, 0x7f800000
	s_brev_b32 s30, 32
	s_brev_b32 s31, 16
	s_brev_b32 s34, 48
	s_mov_b32 s35, 0xf800000
	v_mov_b32_e32 v1, 0x260
	s_brev_b32 s36, 12
	v_mov_b32_e32 v52, 0x41b17218
	v_readlane_b32 s58, v239, 34
	v_readlane_b32 s59, v239, 35
	v_readlane_b32 s60, v239, 36
	v_readlane_b32 s61, v239, 37
	v_readlane_b32 s62, v239, 38
	v_readlane_b32 s63, v239, 39
	v_readlane_b32 s64, v239, 40
	v_readlane_b32 s65, v239, 41
	v_readlane_b32 s66, v239, 42
	v_readlane_b32 s67, v239, 43
	s_branch .LBB0_469
.LBB0_468:
	s_or_b64 exec, exec, s[4:5]
	s_add_i32 s12, s12, s14
	s_add_u32 s18, s18, s20
	s_addc_u32 s19, s19, s21
	s_add_u32 s22, s22, s20
	s_addc_u32 s23, s23, s21
	s_add_u32 s24, s24, s13
	s_addc_u32 s25, s25, s15
	s_and_b32 s4, s12, 63
	s_cmp_lg_u32 s4, 0
	v_lshl_add_u64 v[36:37], v[36:37], 0, s[16:17]
	s_cbranch_scc0 .LBB0_474
.LBB0_469:
	v_lshl_add_u64 v[38:39], s[24:25], 0, v[34:35]
	v_add_co_u32_e32 v40, vcc, 0xf000000, v38
	s_and_b32 s4, s12, 0x3fff
	s_nop 0
	v_addc_co_u32_e32 v41, vcc, 0, v39, vcc
	v_add_co_u32_e32 v42, vcc, 0xf001000, v38
	s_cmp_eq_u32 s4, 0
	s_nop 0
	v_addc_co_u32_e32 v43, vcc, 0, v39, vcc
	global_load_dwordx2 v[48:49], v[40:41], off
	global_load_dwordx2 v[44:45], v[40:41], off offset:2048
	s_nop 0
	global_load_dwordx2 v[40:41], v[42:43], off
	s_and_b32 s5, s12, 63
	s_cmp_lg_u32 s5, 0
	s_cbranch_scc1 .Lp4_reuse
	s_cmp_eq_u32 s4, 0
	s_cbranch_scc1 .LBB0_471
	v_add_co_u32_e32 v42, vcc, 0xeffe000, v38
	s_nop 1
	v_addc_co_u32_e32 v43, vcc, 0, v39, vcc
	v_add_co_u32_e32 v38, vcc, 0xefff000, v38
	s_nop 1
	v_addc_co_u32_e32 v39, vcc, 0, v39, vcc
	global_load_dwordx2 v[50:51], v[42:43], off offset:1536
	global_load_dwordx2 v[46:47], v[42:43], off offset:3584
	s_nop 0
	global_load_dwordx2 v[42:43], v[38:39], off offset:1536
	s_branch .LBB0_472
.Lp4_reuse:
	v_mov_b32_e32 v50, v100
	v_mov_b32_e32 v51, v101
	v_mov_b32_e32 v46, v102
	v_mov_b32_e32 v47, v103
	v_mov_b32_e32 v42, v104
	v_mov_b32_e32 v43, v105
	s_branch .LBB0_472

.LBB0_472:
	v_lshl_add_u64 v[38:39], s[18:19], 0, v[34:35]
	v_add_co_u32_e32 v54, vcc, 0x38000000, v38
	s_nop 1
	v_addc_co_u32_e32 v55, vcc, 0, v39, vcc
	global_load_dwordx2 v[54:55], v[54:55], off
	v_add_co_u32_e32 v56, vcc, 0x3c000000, v38
	s_nop 1
	v_addc_co_u32_e32 v57, vcc, 0, v39, vcc
	global_load_dwordx2 v[56:57], v[56:57], off
	s_waitcnt vmcnt(0)
	v_mov_b32_e32 v100, v48
	v_mov_b32_e32 v101, v49
	v_mov_b32_e32 v102, v44
	v_mov_b32_e32 v103, v45
	v_mov_b32_e32 v104, v40
	v_mov_b32_e32 v105, v41
	v_cvt_f32_f16_e32 v53, v54
	v_cvt_f32_f16_sdwa v54, v54 dst_sel:DWORD dst_unused:UNUSED_PAD src0_sel:WORD_1
	v_cvt_f32_f16_e32 v58, v55
	v_cvt_f32_f16_sdwa v55, v55 dst_sel:DWORD dst_unused:UNUSED_PAD src0_sel:WORD_1
	v_add_f32_e32 v53, v14, v53
	v_add_f32_e32 v54, v15, v54
	v_cvt_f32_f16_e32 v59, v56
	v_cvt_f32_f16_sdwa v56, v56 dst_sel:DWORD dst_unused:UNUSED_PAD src0_sel:WORD_1
	v_max_f32_e64 v61, -v53, 0
	v_mul_f32_e64 v53, |v53|, s26
	v_add_f32_e32 v58, v16, v58
	v_max_f32_e64 v62, -v54, 0
	v_mul_f32_e64 v54, |v54|, s26
	v_exp_f32_e32 v53, v53
	v_add_f32_e32 v55, v17, v55
	v_max_f32_e64 v63, -v58, 0
	v_mul_f32_e64 v58, |v58|, s26
	v_exp_f32_e32 v65, v54
	v_max_f32_e64 v64, -v55, 0
	v_mul_f32_e64 v55, |v55|, s26
	v_exp_f32_e32 v58, v58
	v_add_f32_e32 v56, v11, v56
	v_exp_f32_e32 v66, v55
	v_mul_f32_e32 v56, 0xbfb8aa3b, v56
	v_add_f32_e32 v53, 1.0, v53
	v_add_f32_e32 v59, v10, v59
	v_exp_f32_e32 v55, v56
	v_add_f32_e32 v56, 1.0, v65
	v_cmp_gt_f32_e32 vcc, s27, v53
	v_mul_f32_e32 v59, 0xbfb8aa3b, v59
	v_add_f32_e32 v58, 1.0, v58
	v_cndmask_b32_e64 v65, 0, 32, vcc
	v_cmp_gt_f32_e64 s[4:5], s27, v56
	v_exp_f32_e32 v54, v59
	v_add_f32_e32 v59, 1.0, v66
	v_cndmask_b32_e64 v66, 0, 32, s[4:5]
	v_cmp_gt_f32_e64 s[6:7], s27, v58
	v_ldexp_f32 v53, v53, v65
	v_ldexp_f32 v56, v56, v66
	v_cndmask_b32_e64 v67, 0, 32, s[6:7]
	v_log_f32_e32 v53, v53
	v_ldexp_f32 v58, v58, v67
	v_log_f32_e32 v56, v56
	v_log_f32_e32 v58, v58
	v_cmp_gt_f32_e64 s[8:9], s27, v59
	v_mul_f32_e32 v69, 0x3f317217, v53
	v_mul_f32_e32 v70, 0x3f317217, v56
	v_cndmask_b32_e64 v68, 0, 32, s[8:9]
	v_ldexp_f32 v59, v59, v68
	v_fma_f32 v69, v53, s28, -v69
	v_log_f32_e32 v59, v59
	v_mul_f32_e32 v71, 0x3f317217, v58
	v_fma_f32 v70, v56, s28, -v70
	v_fmac_f32_e32 v69, 0x3377d1cf, v53
	v_cndmask_b32_e32 v65, 0, v52, vcc
	v_fma_f32 v71, v58, s28, -v71
	v_fmac_f32_e32 v70, 0x3377d1cf, v56
	v_fmac_f32_e32 v69, 0x3f317217, v53
	v_cmp_lt_f32_e64 vcc, |v53|, s29
	v_fmac_f32_e32 v71, 0x3377d1cf, v58
	v_fmac_f32_e32 v70, 0x3f317217, v56
	v_cndmask_b32_e32 v53, v53, v69, vcc
	v_cmp_lt_f32_e64 vcc, |v56|, s29
	v_cndmask_b32_e64 v66, 0, v52, s[4:5]
	v_fmac_f32_e32 v71, 0x3f317217, v58
	v_cndmask_b32_e32 v56, v56, v70, vcc
	v_cmp_lt_f32_e64 vcc, |v58|, s29
	v_cndmask_b32_e64 v67, 0, v52, s[6:7]
	v_mul_f32_e32 v72, 0x3f317217, v59
	v_cndmask_b32_e32 v58, v58, v71, vcc
	v_sub_f32_e32 v56, v56, v66
	v_fma_f32 v72, v59, s28, -v72
	v_sub_f32_e32 v58, v58, v67
	v_add_f32_e32 v56, v62, v56
	v_fmac_f32_e32 v72, 0x3377d1cf, v59
	v_add_f32_e32 v58, v63, v58
	v_sub_f32_e32 v56, -0.5, v56
	v_fmac_f32_e32 v72, 0x3f317217, v59
	v_cmp_lt_f32_e64 vcc, |v59|, s29
	v_sub_f32_e32 v58, -0.5, v58
	v_mul_f32_e32 v56, 0x3fb8aa3b, v56
	v_cndmask_b32_e64 v68, 0, v52, s[8:9]
	v_cndmask_b32_e32 v59, v59, v72, vcc
	v_mul_f32_e32 v58, 0x3fb8aa3b, v58
	v_exp_f32_e32 v56, v56
	v_sub_f32_e32 v59, v59, v68
	v_exp_f32_e32 v58, v58
	v_add_f32_e32 v59, v64, v59
	v_sub_f32_e32 v59, -0.5, v59
	v_mul_f32_e32 v59, 0x3fb8aa3b, v59
	v_mul_f32_e32 v56, 0xbfb8aa3b, v56
	v_mul_f32_e32 v58, 0xbfb8aa3b, v58
	v_exp_f32_e32 v56, v56
	v_exp_f32_e32 v59, v59
	v_sub_f32_e32 v53, v53, v65
	v_exp_f32_e32 v58, v58
	v_add_f32_e32 v53, v61, v53
	v_sub_f32_e32 v53, -0.5, v53
	v_cvt_f32_f16_e32 v60, v57
	v_mul_f32_e32 v53, 0x3fb8aa3b, v53
	v_sub_f32_e32 v62, 1.0, v56
	v_mul_f32_e32 v56, 0xbfb8aa3b, v59
	v_exp_f32_e32 v53, v53
	v_sub_f32_e32 v63, 1.0, v58
	v_exp_f32_e32 v58, v56
	v_add_f32_e32 v60, v12, v60
	v_mul_f32_e32 v53, 0xbfb8aa3b, v53
	v_mul_f32_e32 v56, 0xbfb8aa3b, v60
	v_sub_f32_e32 v64, 1.0, v58
	v_lshlrev_b32_e32 v58, 16, v48
	v_and_b32_e32 v59, 0xffff0000, v48
	v_lshlrev_b32_e32 v60, 16, v50
	v_and_b32_e32 v61, 0xffff0000, v50
	v_exp_f32_e32 v53, v53
	v_pk_add_f32 v[60:61], v[60:61], v[58:59] neg_lo:[0,1] neg_hi:[0,1]
	v_lshlrev_b32_e32 v50, 16, v51
	v_pk_fma_f32 v[58:59], v[30:31], v[60:61], v[58:59]
	v_lshlrev_b32_e32 v60, 16, v49
	v_and_b32_e32 v61, 0xffff0000, v49
	v_and_b32_e32 v51, 0xffff0000, v51
	v_pk_add_f32 v[50:51], v[50:51], v[60:61] neg_lo:[0,1] neg_hi:[0,1]
	v_sub_f32_e32 v53, 1.0, v53
	v_pk_fma_f32 v[50:51], v[32:33], v[50:51], v[60:61]
	v_cvt_pk_f16_f32 v48, v58, v59
	v_cvt_pk_f16_f32 v49, v50, v51
	v_lshl_add_u64 v[60:61], s[22:23], 0, v[34:35]
	global_store_dwordx2 v[60:61], v[48:49], off nt
	v_cvt_pk_f16_f32 v48, v53, v62
	v_add_co_u32_e32 v62, vcc, s30, v60
	v_cvt_pk_f16_f32 v49, v63, v64
	s_nop 0
	v_addc_co_u32_e32 v63, vcc, 0, v61, vcc
	v_pk_add_f32 v[54:55], v[54:55], 1.0 op_sel_hi:[1,0]
	global_store_dwordx2 v[62:63], v[48:49], off nt
	v_lshlrev_b32_e32 v48, 16, v44
	v_and_b32_e32 v49, 0xffff0000, v44
	v_div_scale_f32 v44, s[4:5], v55, v55, 1.0
	v_rcp_f32_e32 v53, v44
	v_lshlrev_b32_e32 v62, 16, v46
	v_and_b32_e32 v63, 0xffff0000, v46
	v_pk_add_f32 v[62:63], v[62:63], v[48:49] neg_lo:[0,1] neg_hi:[0,1]
	v_fma_f32 v46, -v44, v53, 1.0
	v_fmac_f32_e32 v53, v46, v53
	v_div_scale_f32 v46, vcc, 1.0, v55, 1.0
	v_pk_fma_f32 v[48:49], v[22:23], v[62:63], v[48:49]
	v_mul_f32_e32 v62, v46, v53
	v_fma_f32 v63, -v44, v62, v46
	v_fmac_f32_e32 v62, v63, v53
	v_fma_f32 v44, -v44, v62, v46
	v_div_scale_f32 v46, s[4:5], v54, v54, 1.0
	v_rcp_f32_e32 v63, v46
	v_div_fmas_f32 v44, v44, v53, v62
	v_cvt_f32_f16_sdwa v57, v57 dst_sel:DWORD dst_unused:UNUSED_PAD src0_sel:WORD_1
	v_div_fixup_f32 v55, v44, v55, 1.0
	v_fma_f32 v44, -v46, v63, 1.0
	v_fmac_f32_e32 v63, v44, v63
	v_div_scale_f32 v44, vcc, 1.0, v54, 1.0
	v_mul_f32_e32 v53, v44, v63
	v_fma_f32 v62, -v46, v53, v44
	v_add_f32_e32 v57, v13, v57
	v_fmac_f32_e32 v53, v62, v63
	v_mul_f32_e32 v57, 0xbfb8aa3b, v57
	v_fma_f32 v44, -v46, v53, v44
	v_exp_f32_e32 v56, v56
	v_exp_f32_e32 v57, v57
	v_div_fmas_f32 v44, v44, v63, v53
	v_div_fixup_f32 v54, v44, v54, 1.0
	v_pk_add_f32 v[62:63], v[54:55], -1.0 op_sel_hi:[1,0]
	v_pk_add_f32 v[56:57], v[56:57], 1.0 op_sel_hi:[1,0]
	v_pk_fma_f32 v[62:63], v[2:3], v[62:63], 1.0 op_sel_hi:[1,1,0]
	v_lshlrev_b32_e32 v44, 16, v45
	v_pk_mul_f32 v[62:63], v[48:49], v[62:63]
	v_and_b32_e32 v45, 0xffff0000, v45
	v_pk_mul_f32 v[58:59], v[58:59], v[62:63]
	v_cvt_pk_f16_f32 v46, v62, v63
	v_div_scale_f32 v62, s[4:5], v57, v57, 1.0
	v_rcp_f32_e32 v63, v62
	v_fma_f32 v53, v26, v58, 0
	v_fmac_f32_e32 v53, v27, v59
	v_lshlrev_b32_e32 v58, 16, v47
	v_and_b32_e32 v59, 0xffff0000, v47
	v_pk_add_f32 v[58:59], v[58:59], v[44:45] neg_lo:[0,1] neg_hi:[0,1]
	v_pk_mul_f32 v[48:49], v[6:7], v[48:49]
	v_pk_fma_f32 v[58:59], v[24:25], v[58:59], v[44:45]
	v_fma_f32 v44, -v62, v63, 1.0
	v_fmac_f32_e32 v63, v44, v63
	v_div_scale_f32 v44, vcc, 1.0, v57, 1.0
	v_mul_f32_e32 v45, v44, v63
	v_fma_f32 v47, -v62, v45, v44
	v_fmac_f32_e32 v45, v47, v63
	v_div_scale_f32 v47, s[4:5], v56, v56, 1.0
	v_fma_f32 v44, -v62, v45, v44
	v_rcp_f32_e32 v62, v47
	v_div_fmas_f32 v44, v44, v63, v45
	v_div_fixup_f32 v57, v44, v57, 1.0
	v_fma_f32 v44, -v47, v62, 1.0
	v_fmac_f32_e32 v62, v44, v62
	v_div_scale_f32 v44, vcc, 1.0, v56, 1.0
	v_mul_f32_e32 v45, v44, v62
	v_fma_f32 v63, -v47, v45, v44
	v_fmac_f32_e32 v45, v63, v62
	v_fma_f32 v44, -v47, v45, v44
	v_div_fmas_f32 v44, v44, v62, v45
	v_div_fixup_f32 v56, v44, v56, 1.0
	v_pk_add_f32 v[44:45], v[56:57], -1.0 op_sel_hi:[1,0]
	s_nop 0
	v_pk_fma_f32 v[44:45], v[4:5], v[44:45], 1.0 op_sel_hi:[1,1,0]
	s_nop 0
	v_pk_mul_f32 v[62:63], v[58:59], v[44:45]
	s_nop 0
	v_pk_mul_f32 v[44:45], v[50:51], v[62:63]
	v_add_co_u32_e32 v50, vcc, s31, v60
	v_cvt_pk_f16_f32 v47, v62, v63
	s_nop 0
	v_addc_co_u32_e32 v51, vcc, 0, v61, vcc
	global_store_dwordx2 v[50:51], v[46:47], off nt
	v_lshlrev_b32_e32 v46, 16, v40
	v_and_b32_e32 v47, 0xffff0000, v40
	v_lshlrev_b32_e32 v50, 16, v42
	v_and_b32_e32 v51, 0xffff0000, v42
	v_pk_add_f32 v[50:51], v[50:51], v[46:47] neg_lo:[0,1] neg_hi:[0,1]
	v_pk_mul_f32 v[62:63], v[48:49], v[48:49]
	v_pk_fma_f32 v[46:47], v[18:19], v[50:51], v[46:47]
	v_pk_mul_f32 v[50:51], v[8:9], v[58:59]
	v_cvt_pk_f16_f32 v40, v46, v47
	v_lshlrev_b32_e32 v46, 16, v41
	v_and_b32_e32 v47, 0xffff0000, v41
	v_pk_mul_f32 v[58:59], v[50:51], v[50:51]
	v_add_f32_e32 v41, v62, v63
	v_add_f32_e32 v41, v58, v41
	v_add_f32_e32 v41, v59, v41
	v_fmac_f32_e32 v53, v28, v44
	v_fmac_f32_e32 v53, v29, v45
	v_add_f32_dpp v41, v41, v41 row_ror:8 row_mask:0xf bank_mask:0xf bound_ctrl:1
	v_lshlrev_b32_e32 v42, 16, v43
	v_add_f32_dpp v44, v53, v53 row_ror:8 row_mask:0xf bank_mask:0xf bound_ctrl:1
	v_add_f32_dpp v41, v41, v41 row_ror:4 row_mask:0xf bank_mask:0xf bound_ctrl:1
	v_and_b32_e32 v43, 0xffff0000, v43
	v_pk_add_f32 v[42:43], v[42:43], v[46:47] neg_lo:[0,1] neg_hi:[0,1]
	v_add_f32_dpp v41, v41, v41 row_ror:2 row_mask:0xf bank_mask:0xf bound_ctrl:1
	v_pk_fma_f32 v[42:43], v[20:21], v[42:43], v[46:47]
	v_add_f32_dpp v44, v44, v44 row_ror:4 row_mask:0xf bank_mask:0xf bound_ctrl:1
	v_add_f32_dpp v41, v41, v41 row_ror:1 row_mask:0xf bank_mask:0xf bound_ctrl:1
	v_mul_f32_e32 v53, 0x4f800000, v41
	v_cmp_gt_f32_e32 vcc, s35, v41
	v_add_f32_dpp v44, v44, v44 row_ror:2 row_mask:0xf bank_mask:0xf bound_ctrl:1
	s_nop 0
	v_cndmask_b32_e32 v53, v41, v53, vcc
	v_sqrt_f32_e32 v58, v53
	v_cvt_pk_f16_f32 v41, v42, v43
	v_mov_b32_dpp v45, v44 row_ror:1 row_mask:0xf bank_mask:0xf bound_ctrl:1
	v_add_u32_e32 v42, -1, v58
	v_fma_f32 v43, -v42, v58, v53
	v_cmp_ge_f32_e64 s[4:5], 0, v43
	v_add_u32_e32 v43, 1, v58
	v_fma_f32 v46, -v43, v58, v53
	v_cndmask_b32_e64 v42, v58, v42, s[4:5]
	v_cmp_lt_f32_e64 s[4:5], 0, v46
	s_nop 1
	v_cndmask_b32_e64 v42, v42, v43, s[4:5]
	v_mul_f32_e32 v43, 0x37800000, v42
	v_cndmask_b32_e32 v42, v42, v43, vcc
	v_cmp_class_f32_e32 vcc, v53, v1
	s_nop 1
	v_cndmask_b32_e32 v42, v42, v53, vcc
	v_max_f32_e32 v46, 0x2b8cbccc, v42
	v_div_scale_f32 v47, s[4:5], v46, v46, 1.0
	v_rcp_f32_e32 v53, v47
	v_add_co_u32_e32 v42, vcc, s34, v60
	s_nop 1
	v_addc_co_u32_e32 v43, vcc, 0, v61, vcc
	global_store_dwordx2 v[42:43], v[40:41], off nt
	v_fma_f32 v40, -v47, v53, 1.0
	v_fmac_f32_e32 v53, v40, v53
	v_div_scale_f32 v40, vcc, 1.0, v46, 1.0
	v_mul_f32_e32 v41, v40, v53
	v_fma_f32 v42, -v47, v41, v40
	v_fmac_f32_e32 v41, v42, v53
	v_fma_f32 v40, -v47, v41, v40
	v_div_fmas_f32 v40, v40, v53, v41
	v_div_fixup_f32 v40, v40, v46, 1.0
	v_pk_mul_f32 v[42:43], v[48:49], v[40:41] op_sel_hi:[1,0]
	v_add_co_u32_e32 v48, vcc, s36, v38
	v_pk_mul_f32 v[40:41], v[50:51], v[40:41] op_sel_hi:[1,0]
	s_nop 0
	v_addc_co_u32_e32 v49, vcc, 0, v39, vcc
	v_cvt_pk_f16_f32 v46, v42, v43
	v_cvt_pk_f16_f32 v47, v40, v41
	v_pk_mul_f32 v[42:43], v[54:55], v[42:43]
	v_pk_mul_f32 v[40:41], v[56:57], v[40:41]
	v_add_co_u32_e32 v38, vcc, 0x34000000, v38
	v_cvt_pk_f16_f32 v42, v42, v43
	v_cvt_pk_f16_f32 v43, v40, v41
	v_addc_co_u32_e32 v39, vcc, 0, v39, vcc
	global_store_dwordx2 v[48:49], v[46:47], off nt
	global_store_dwordx2 v[38:39], v[42:43], off nt
	s_and_saveexec_b64 s[4:5], s[0:1]
	s_cbranch_execz .LBB0_468
	v_add_f32_e32 v38, v44, v45
	global_store_dword v[36:37], v38, off
	s_branch .LBB0_468
